# PEER u-side and v-side fused into one hand-written phase: workgroup owns 32 tokens, sweeps the 8 slices of each fp8 table, per-token dots accumulate in LDS, act formed in-block; the 8 partial slabs, t
# speedup vs baseline: 1.1728x; 1.0551x over previous
; DI unsigned xb_ld(unsigned* p) { return __hip_atomic_load(p, __ATOMIC_RELAXED, __HIP_MEMORY_SCOPE_AGENT); }
; DI unsigned xb_xcc_id() { return (unsigned)__builtin_amdgcn_s_getreg((3 << 11) | 20) & 0xFu; }
; DI void phase_peer_u(const Params& p, char* smem) {
;   const int tid = threadIdx.x, lane = tid & 63, wave = tid >> 6;
;   const int pg = lane >> 3, cq = lane & 7;
;   const unsigned xcc = xb_xcc_id() & 7u;
;   volatile int* qslot = (volatile int*)smem;
;   unsigned* cnt = p.bar + 4096;
;   const bool b0 = (lane & 1) != 0, b1 = (lane & 2) != 0, b2 = (lane & 4) != 0;
;   const int ibase = (b0 ? 8 : 0) + (b1 ? 4 : 0) + (b2 ? 2 : 0);
;   for (int pi = 0; pi < 8; pi++) {
;     const int slice = (int)((xcc + (unsigned)pi) & 7u);
;     const unsigned char* ubase = p.ub8 + (size_t)slice * 16384 * 128 + cq * 16;
;     float* pbase = p.part + (size_t)slice * T_TOK * 128;
;     for (;;) {
;       __syncthreads();
;       if (tid == 0) {
;         const unsigned c0 = (pi >= 1) ? xb_ld(&cnt[slice]) : 0u;
;         qslot[0] = (c0 >= 64u) ? 64 : (int)atomicAdd(&cnt[slice], 1u);
;       }
;       __syncthreads();
;       const int tile = qslot[0];
;       if (tile >= 64) break;
;       const int tb = tile * 256 + wave * 64;
;       int e0a = p.experts[(size_t)tb * 128 + lane], e0b = p.experts[(size_t)tb * 128 + 64 + lane];
;       int e1a = p.experts[(size_t)(tb + 1) * 128 + lane], e1b = p.experts[(size_t)(tb + 1) * 128 + 64 + lane];
;       u32x4 h0a = *(const u32x4*)(p.hn + (size_t)tb * 1024 + slice * 128 + cq * 16);
;       u32x4 h0b = *(const u32x4*)(p.hn + (size_t)tb * 1024 + slice * 128 + cq * 16 + 8);
.LBB0_1316:
	s_cmp_gt_i32 s48, 9
	s_cselect_b64 s[0:1], -1, 0
	s_cmp_lt_i32 s49, 10
	s_cselect_b64 s[2:3], -1, 0
	s_or_b64 s[0:1], s[0:1], s[2:3]
	s_and_b64 vcc, exec, s[0:1]
	v_bfe_u32 v180, v0, 3, 3
	v_and_b32_e32 v146, 63, v0
	v_mbcnt_lo_u32_b32 v181, -1, 0
	s_cbranch_vccnz .LBB0_1412
	v_and_b32_e32 v1, 0x3ff, v0
	v_and_b32_e32 v2, 63, v1
	v_lshlrev_b32_e32 v3, 4, v2
	v_and_b32_e32 v3, 0x70, v3
	v_lshrrev_b32_e32 v4, 3, v2
	v_lshrrev_b32_e32 v5, 6, v1
	v_readlane_b32 s2, v253, 10
	v_readlane_b32 s3, v253, 11
	v_readlane_b32 s33, v253, 8
	s_sub_u32 s2, s2, 0x1c8
	s_subb_u32 s3, s3, 0
	s_load_dwordx2 s[4:5], s[2:3], 0x88
	s_load_dwordx2 s[6:7], s[2:3], 0x190
	s_load_dwordx2 s[8:9], s[2:3], 0x188
	s_load_dwordx2 s[10:11], s[2:3], 0x1a8
	s_load_dwordx2 s[12:13], s[2:3], 0x150
	s_load_dwordx2 s[14:15], s[2:3], 0x1b8
	s_load_dwordx2 s[58:59], s[2:3], 0x130
	s_getreg_b32 s16, hwreg(HW_REG_XCC_ID, 0, 4)
	s_and_b32 s16, s16, 7
	v_mul_u32_u24_e32 v228, 0x3000, v5
	v_add_u32_e32 v228, 0x400, v228
	v_and_b32_e32 v6, 7, v2
	v_lshlrev_b32_e32 v6, 4, v6
	v_add_u32_e32 v6, v6, v4
	v_lshl_add_u32 v229, v6, 2, v228
	v_lshl_add_u32 v241, v2, 3, v228
	v_and_b32_e32 v6, 1, v2
	v_lshlrev_b32_e32 v6, 3, v6
	v_and_b32_e32 v7, 2, v2
	v_lshl_or_b32 v6, v7, 1, v6
	v_and_b32_e32 v7, 4, v2
	v_lshrrev_b32_e32 v7, 1, v7
	v_or_b32_e32 v6, v6, v7
	v_lshl_add_u32 v7, v4, 4, v6
	v_lshl_add_u32 v238, v7, 2, v228
	v_and_b32_e32 v7, 7, v6
	v_lshl_add_u32 v7, v7, 3, v4
	v_lshrrev_b32_e32 v6, 3, v6
	v_lshl_add_u32 v7, v6, 6, v7
	v_lshlrev_b32_e32 v239, 2, v7
	v_lshl_add_u32 v228, v4, 6, v228
	v_xor_b32_e32 v230, 16, v2
	v_lshlrev_b32_e32 v230, 2, v230
	v_lshrrev_b32_e32 v6, 2, v2
	v_and_b32_e32 v6, 14, v6
	v_add_u32_e32 v6, v6, v3
	v_lshlrev_b32_e32 v231, 2, v6
	v_lshlrev_b32_e32 v237, 2, v2
	v_lshlrev_b32_e32 v240, 1, v3
	v_and_b32_e32 v6, 16, v2
	v_cmp_eq_u32_e64 s[52:53], 0, v6
	v_and_b32_e32 v6, 8, v2
	v_cmp_eq_u32_e64 s[54:55], 0, v6
	v_and_b32_e32 v6, 1, v2
	v_cmp_eq_u32_e64 s[60:61], 0, v6
	v_and_b32_e32 v6, 2, v2
	v_cmp_eq_u32_e64 s[62:63], 0, v6
	v_and_b32_e32 v6, 4, v2
	v_cmp_eq_u32_e64 s[64:65], 0, v6
	v_readfirstlane_b32 s34, v5
	s_lshl_b32 s34, s34, 3
	s_mov_b32 s18, s100
	s_waitcnt lgkmcnt(0)
.Lpeer_group:
	s_lshl_b32 s19, s18, 5
	s_add_u32 s19, s19, s34
	s_add_u32 s35, s19, 0
	s_lshl_b32 s35, s35, 9
	s_add_u32 s36, s14, s35
	s_addc_u32 s37, s15, 0
	global_load_dword v160, v237, s[36:37]
	global_load_dword v161, v237, s[36:37] offset:256
	s_add_u32 s35, s19, 1
	s_lshl_b32 s35, s35, 9
	s_add_u32 s36, s14, s35
	s_addc_u32 s37, s15, 0
	global_load_dword v162, v237, s[36:37]
	global_load_dword v163, v237, s[36:37] offset:256
	s_add_u32 s35, s19, 2
	s_lshl_b32 s35, s35, 9
	s_add_u32 s36, s14, s35
	s_addc_u32 s37, s15, 0
	global_load_dword v164, v237, s[36:37]
	global_load_dword v165, v237, s[36:37] offset:256
	s_add_u32 s35, s19, 3
	s_lshl_b32 s35, s35, 9
	s_add_u32 s36, s14, s35
	s_addc_u32 s37, s15, 0
	global_load_dword v166, v237, s[36:37]
	global_load_dword v167, v237, s[36:37] offset:256
	s_add_u32 s35, s19, 4
	s_lshl_b32 s35, s35, 9
	s_add_u32 s36, s14, s35
	s_addc_u32 s37, s15, 0
	global_load_dword v168, v237, s[36:37]
	global_load_dword v169, v237, s[36:37] offset:256
	s_add_u32 s35, s19, 5
	s_lshl_b32 s35, s35, 9
	s_add_u32 s36, s14, s35
	s_addc_u32 s37, s15, 0
	global_load_dword v170, v237, s[36:37]
	global_load_dword v171, v237, s[36:37] offset:256
	s_add_u32 s35, s19, 6
	s_lshl_b32 s35, s35, 9
	s_add_u32 s36, s14, s35
	s_addc_u32 s37, s15, 0
	global_load_dword v172, v237, s[36:37]
	global_load_dword v173, v237, s[36:37] offset:256
	s_add_u32 s35, s19, 7
	s_lshl_b32 s35, s35, 9
	s_add_u32 s36, s14, s35
	s_addc_u32 s37, s15, 0
	global_load_dword v174, v237, s[36:37]
	global_load_dword v175, v237, s[36:37] offset:256
	v_mov_b32_e32 v6, 0
	v_mov_b32_e32 v7, 0
	ds_write_b64 v241, v[6:7] offset:8192
	ds_write_b64 v241, v[6:7] offset:8704
	ds_write_b64 v241, v[6:7] offset:9216
	ds_write_b64 v241, v[6:7] offset:9728
	ds_write_b64 v241, v[6:7] offset:10240
	ds_write_b64 v241, v[6:7] offset:10752
	ds_write_b64 v241, v[6:7] offset:11264
	ds_write_b64 v241, v[6:7] offset:11776
	s_waitcnt vmcnt(0)
	v_lshlrev_b32_e32 v160, 7, v160
	v_lshlrev_b32_e32 v161, 7, v161
	ds_write_b32 v229, v160 offset:4096
	ds_write_b32 v229, v161 offset:4128
	v_lshlrev_b32_e32 v162, 7, v162
	v_lshlrev_b32_e32 v163, 7, v163
	ds_write_b32 v229, v162 offset:4608
	ds_write_b32 v229, v163 offset:4640
	v_lshlrev_b32_e32 v164, 7, v164
	v_lshlrev_b32_e32 v165, 7, v165
	ds_write_b32 v229, v164 offset:5120
	ds_write_b32 v229, v165 offset:5152
	v_lshlrev_b32_e32 v166, 7, v166
	v_lshlrev_b32_e32 v167, 7, v167
	ds_write_b32 v229, v166 offset:5632
	ds_write_b32 v229, v167 offset:5664
	v_lshlrev_b32_e32 v168, 7, v168
	v_lshlrev_b32_e32 v169, 7, v169
	ds_write_b32 v229, v168 offset:6144
	ds_write_b32 v229, v169 offset:6176
	v_lshlrev_b32_e32 v170, 7, v170
	v_lshlrev_b32_e32 v171, 7, v171
	ds_write_b32 v229, v170 offset:6656
	ds_write_b32 v229, v171 offset:6688
	v_lshlrev_b32_e32 v172, 7, v172
	v_lshlrev_b32_e32 v173, 7, v173
	ds_write_b32 v229, v172 offset:7168
	ds_write_b32 v229, v173 offset:7200
	v_lshlrev_b32_e32 v174, 7, v174
	v_lshlrev_b32_e32 v175, 7, v175
	ds_write_b32 v229, v174 offset:7680
	ds_write_b32 v229, v175 offset:7712
	s_waitcnt lgkmcnt(0)
	ds_read_b128 v[128:131], v228 offset:4096
	ds_read_b128 v[132:135], v228 offset:4112
	ds_read_b128 v[136:139], v228 offset:4128
	ds_read_b128 v[140:143], v228 offset:4144
	s_lshl_b32 s24, s16, 21
	s_add_u32 s20, s8, s24
	s_addc_u32 s21, s9, 0
	s_lshl_b32 s31, s19, 11
	s_lshl_b32 s32, s16, 8
	s_add_u32 s31, s31, s32
	s_add_u32 s22, s58, s31
	s_addc_u32 s23, s59, 0
	global_load_dwordx4 v[104:107], v240, s[22:23]
	global_load_dwordx4 v[108:111], v240, s[22:23] offset:16
	s_waitcnt lgkmcnt(0)
; DI void phase_peer_u(const Params& p, char* smem) {
;     ...
;       u32x4 R0[16], R1[16];
; #pragma unroll
;       for (int i = 0; i < 16; i++) {
;         const int e = __shfl(i < 8 ? e0a : e0b, 8 * (i & 7) + pg);
;         R0[i] = *(const u32x4*)(ubase + (size_t)e * 128);
;       }
;       for (int tl = 0; tl < 64; tl++) {
;         const int t = tb + tl;
;         const int t1 = tb + min(tl + 1, 63), t2 = tb + min(tl + 2, 63);
;         const int e2a = p.experts[(size_t)t2 * 128 + lane], e2b = p.experts[(size_t)t2 * 128 + 64 + lane];
;         const u32x4 h1a = *(const u32x4*)(p.hn + (size_t)t1 * 1024 + slice * 128 + cq * 16);
;         const u32x4 h1b = *(const u32x4*)(p.hn + (size_t)t1 * 1024 + slice * 128 + cq * 16 + 8);
; #pragma unroll
;         for (int i = 0; i < 16; i++) {
;           const int e = __shfl(i < 8 ? e1a : e1b, 8 * (i & 7) + pg);
;           R1[i] = *(const u32x4*)(ubase + (size_t)e * 128);
;         }
;         __builtin_amdgcn_sched_barrier(0);
;         float x[16];
;         unpack8(h0a, x); unpack8(h0b, x + 8);
;         f32x2 xr[8];
; #pragma unroll
;         for (int j = 0; j < 8; j++) { xr[j].x = x[2 * j]; xr[j].y = x[2 * j + 1]; }
;         float d[16];
; #pragma unroll
;         for (int i = 0; i < 16; i++) {
;           f32x2 uf[8];
;           unpack_fp8x16(R0[i], uf);
;           f32x2 acc2 = uf[0] * xr[0];
; #pragma unroll
;           for (int j = 1; j < 8; j++) acc2 += uf[j] * xr[j];
;           d[i] = acc2.x + acc2.y;
	v_or_b32_e32 v200, v128, v3
	global_load_dwordx4 v[8:11], v200, s[20:21]
	v_or_b32_e32 v201, v129, v3
	global_load_dwordx4 v[12:15], v201, s[20:21]
	v_or_b32_e32 v202, v130, v3
	global_load_dwordx4 v[16:19], v202, s[20:21]
	v_or_b32_e32 v203, v131, v3
	global_load_dwordx4 v[20:23], v203, s[20:21]
	v_or_b32_e32 v200, v132, v3
	global_load_dwordx4 v[24:27], v200, s[20:21]
	v_or_b32_e32 v201, v133, v3
	global_load_dwordx4 v[28:31], v201, s[20:21]
	v_or_b32_e32 v202, v134, v3
	global_load_dwordx4 v[32:35], v202, s[20:21]
	v_or_b32_e32 v203, v135, v3
	global_load_dwordx4 v[36:39], v203, s[20:21]
	v_or_b32_e32 v200, v136, v3
	global_load_dwordx4 v[40:43], v200, s[20:21]
	v_or_b32_e32 v201, v137, v3
	global_load_dwordx4 v[44:47], v201, s[20:21]
	v_or_b32_e32 v202, v138, v3
	global_load_dwordx4 v[48:51], v202, s[20:21]
	v_or_b32_e32 v203, v139, v3
	global_load_dwordx4 v[52:55], v203, s[20:21]
	v_or_b32_e32 v200, v140, v3
	global_load_dwordx4 v[56:59], v200, s[20:21]
	v_or_b32_e32 v201, v141, v3
	global_load_dwordx4 v[60:63], v201, s[20:21]
	v_or_b32_e32 v202, v142, v3
	global_load_dwordx4 v[64:67], v202, s[20:21]
	v_or_b32_e32 v203, v143, v3
	global_load_dwordx4 v[68:71], v203, s[20:21]
	ds_read_b128 v[128:131], v228 offset:4608
	ds_read_b128 v[132:135], v228 offset:4624
	ds_read_b128 v[136:139], v228 offset:4640
	ds_read_b128 v[140:143], v228 offset:4656
	s_mov_b32 s17, 0
	s_waitcnt lgkmcnt(0)
.Lpeer_ustep:
	s_waitcnt vmcnt(16)
	v_lshlrev_b32_e32 v88, 16, v104
	v_and_b32_e32 v89, 0xffff0000, v104
	v_lshlrev_b32_e32 v90, 16, v105
	v_and_b32_e32 v91, 0xffff0000, v105
	v_lshlrev_b32_e32 v92, 16, v106
	v_and_b32_e32 v93, 0xffff0000, v106
	v_lshlrev_b32_e32 v94, 16, v107
	v_and_b32_e32 v95, 0xffff0000, v107
	v_lshlrev_b32_e32 v96, 16, v108
	v_and_b32_e32 v97, 0xffff0000, v108
	v_lshlrev_b32_e32 v98, 16, v109
	v_and_b32_e32 v99, 0xffff0000, v109
	v_lshlrev_b32_e32 v100, 16, v110
	v_and_b32_e32 v101, 0xffff0000, v110
	v_lshlrev_b32_e32 v102, 16, v111
	v_and_b32_e32 v103, 0xffff0000, v111
	s_add_u32 s38, s17, 1
	s_and_b32 s38, s38, 63
	s_lshr_b32 s24, s38, 3
	s_add_u32 s24, s24, s16
	s_and_b32 s24, s24, 7
	s_lshl_b32 s25, s24, 21
	s_add_u32 s20, s8, s25
	s_addc_u32 s21, s9, 0
	s_and_b32 s25, s38, 7
	s_add_u32 s25, s25, s19
	s_lshl_b32 s25, s25, 11
	s_lshl_b32 s24, s24, 8
	s_add_u32 s25, s25, s24
	s_add_u32 s22, s58, s25
	s_addc_u32 s23, s59, 0
	global_load_dwordx4 v[104:107], v240, s[22:23]
	global_load_dwordx4 v[108:111], v240, s[22:23] offset:16
	s_waitcnt vmcnt(17)
	v_cvt_pk_f32_fp8_e32 v[72:73], v8
	v_cvt_pk_f32_fp8_sdwa v[74:75], v8 src0_sel:WORD_1
	v_cvt_pk_f32_fp8_e32 v[76:77], v9
	v_cvt_pk_f32_fp8_sdwa v[78:79], v9 src0_sel:WORD_1
	v_cvt_pk_f32_fp8_e32 v[80:81], v10
	v_cvt_pk_f32_fp8_sdwa v[82:83], v10 src0_sel:WORD_1
	v_cvt_pk_f32_fp8_e32 v[84:85], v11
	v_cvt_pk_f32_fp8_sdwa v[86:87], v11 src0_sel:WORD_1
	v_pk_mul_f32 v[190:191], v[72:73], v[88:89]
	v_pk_fma_f32 v[190:191], v[74:75], v[90:91], v[190:191]
	v_pk_fma_f32 v[190:191], v[76:77], v[92:93], v[190:191]
	v_pk_fma_f32 v[190:191], v[78:79], v[94:95], v[190:191]
	v_pk_fma_f32 v[190:191], v[80:81], v[96:97], v[190:191]
	v_pk_fma_f32 v[190:191], v[82:83], v[98:99], v[190:191]
	v_pk_fma_f32 v[190:191], v[84:85], v[100:101], v[190:191]
	v_pk_fma_f32 v[190:191], v[86:87], v[102:103], v[190:191]
	v_or_b32_e32 v200, v128, v3
	global_load_dwordx4 v[8:11], v200, s[20:21]
	v_add_f32_e32 v112, v190, v191
	s_waitcnt vmcnt(17)
	v_cvt_pk_f32_fp8_e32 v[72:73], v12
	v_cvt_pk_f32_fp8_sdwa v[74:75], v12 src0_sel:WORD_1
	v_cvt_pk_f32_fp8_e32 v[76:77], v13
	v_cvt_pk_f32_fp8_sdwa v[78:79], v13 src0_sel:WORD_1
	v_cvt_pk_f32_fp8_e32 v[80:81], v14
	v_cvt_pk_f32_fp8_sdwa v[82:83], v14 src0_sel:WORD_1
	v_cvt_pk_f32_fp8_e32 v[84:85], v15
	v_cvt_pk_f32_fp8_sdwa v[86:87], v15 src0_sel:WORD_1
	v_pk_mul_f32 v[190:191], v[72:73], v[88:89]
	v_pk_fma_f32 v[190:191], v[74:75], v[90:91], v[190:191]
	v_pk_fma_f32 v[190:191], v[76:77], v[92:93], v[190:191]
	v_pk_fma_f32 v[190:191], v[78:79], v[94:95], v[190:191]
	v_pk_fma_f32 v[190:191], v[80:81], v[96:97], v[190:191]
	v_pk_fma_f32 v[190:191], v[82:83], v[98:99], v[190:191]
	v_pk_fma_f32 v[190:191], v[84:85], v[100:101], v[190:191]
	v_pk_fma_f32 v[190:191], v[86:87], v[102:103], v[190:191]
	v_or_b32_e32 v201, v129, v3
	global_load_dwordx4 v[12:15], v201, s[20:21]
	v_add_f32_e32 v113, v190, v191
	s_waitcnt vmcnt(17)
	v_cvt_pk_f32_fp8_e32 v[72:73], v16
	v_cvt_pk_f32_fp8_sdwa v[74:75], v16 src0_sel:WORD_1
	v_cvt_pk_f32_fp8_e32 v[76:77], v17
	v_cvt_pk_f32_fp8_sdwa v[78:79], v17 src0_sel:WORD_1
	v_cvt_pk_f32_fp8_e32 v[80:81], v18
	v_cvt_pk_f32_fp8_sdwa v[82:83], v18 src0_sel:WORD_1
	v_cvt_pk_f32_fp8_e32 v[84:85], v19
	v_cvt_pk_f32_fp8_sdwa v[86:87], v19 src0_sel:WORD_1
	v_pk_mul_f32 v[190:191], v[72:73], v[88:89]
	v_pk_fma_f32 v[190:191], v[74:75], v[90:91], v[190:191]
	v_pk_fma_f32 v[190:191], v[76:77], v[92:93], v[190:191]
	v_pk_fma_f32 v[190:191], v[78:79], v[94:95], v[190:191]
	v_pk_fma_f32 v[190:191], v[80:81], v[96:97], v[190:191]
	v_pk_fma_f32 v[190:191], v[82:83], v[98:99], v[190:191]
	v_pk_fma_f32 v[190:191], v[84:85], v[100:101], v[190:191]
	v_pk_fma_f32 v[190:191], v[86:87], v[102:103], v[190:191]
	v_or_b32_e32 v202, v130, v3
	global_load_dwordx4 v[16:19], v202, s[20:21]
	v_add_f32_e32 v114, v190, v191
	s_waitcnt vmcnt(17)
; DI void phase_peer_u(const Params& p, char* smem) {
;     ...
;         float d[16];
; #pragma unroll
;         for (int i = 0; i < 16; i++) {
;           f32x2 uf[8];
;           unpack_fp8x16(R0[i], uf);
;           f32x2 acc2 = uf[0] * xr[0];
; #pragma unroll
;           for (int j = 1; j < 8; j++) acc2 += uf[j] * xr[j];
;           d[i] = acc2.x + acc2.y;
;         }
	v_cvt_pk_f32_fp8_e32 v[72:73], v20
	v_cvt_pk_f32_fp8_sdwa v[74:75], v20 src0_sel:WORD_1
	v_cvt_pk_f32_fp8_e32 v[76:77], v21
	v_cvt_pk_f32_fp8_sdwa v[78:79], v21 src0_sel:WORD_1
	v_cvt_pk_f32_fp8_e32 v[80:81], v22
	v_cvt_pk_f32_fp8_sdwa v[82:83], v22 src0_sel:WORD_1
	v_cvt_pk_f32_fp8_e32 v[84:85], v23
	v_cvt_pk_f32_fp8_sdwa v[86:87], v23 src0_sel:WORD_1
	v_pk_mul_f32 v[190:191], v[72:73], v[88:89]
	v_pk_fma_f32 v[190:191], v[74:75], v[90:91], v[190:191]
	v_pk_fma_f32 v[190:191], v[76:77], v[92:93], v[190:191]
	v_pk_fma_f32 v[190:191], v[78:79], v[94:95], v[190:191]
	v_pk_fma_f32 v[190:191], v[80:81], v[96:97], v[190:191]
	v_pk_fma_f32 v[190:191], v[82:83], v[98:99], v[190:191]
	v_pk_fma_f32 v[190:191], v[84:85], v[100:101], v[190:191]
	v_pk_fma_f32 v[190:191], v[86:87], v[102:103], v[190:191]
	v_or_b32_e32 v203, v131, v3
	global_load_dwordx4 v[20:23], v203, s[20:21]
	v_add_f32_e32 v115, v190, v191
	s_waitcnt vmcnt(17)
	v_cvt_pk_f32_fp8_e32 v[72:73], v24
	v_cvt_pk_f32_fp8_sdwa v[74:75], v24 src0_sel:WORD_1
	v_cvt_pk_f32_fp8_e32 v[76:77], v25
	v_cvt_pk_f32_fp8_sdwa v[78:79], v25 src0_sel:WORD_1
	v_cvt_pk_f32_fp8_e32 v[80:81], v26
	v_cvt_pk_f32_fp8_sdwa v[82:83], v26 src0_sel:WORD_1
	v_cvt_pk_f32_fp8_e32 v[84:85], v27
	v_cvt_pk_f32_fp8_sdwa v[86:87], v27 src0_sel:WORD_1
	v_pk_mul_f32 v[190:191], v[72:73], v[88:89]
	v_pk_fma_f32 v[190:191], v[74:75], v[90:91], v[190:191]
	v_pk_fma_f32 v[190:191], v[76:77], v[92:93], v[190:191]
	v_pk_fma_f32 v[190:191], v[78:79], v[94:95], v[190:191]
	v_pk_fma_f32 v[190:191], v[80:81], v[96:97], v[190:191]
	v_pk_fma_f32 v[190:191], v[82:83], v[98:99], v[190:191]
	v_pk_fma_f32 v[190:191], v[84:85], v[100:101], v[190:191]
	v_pk_fma_f32 v[190:191], v[86:87], v[102:103], v[190:191]
	v_or_b32_e32 v200, v132, v3
	global_load_dwordx4 v[24:27], v200, s[20:21]
	v_add_f32_e32 v116, v190, v191
	s_waitcnt vmcnt(17)
	v_cvt_pk_f32_fp8_e32 v[72:73], v28
	v_cvt_pk_f32_fp8_sdwa v[74:75], v28 src0_sel:WORD_1
	v_cvt_pk_f32_fp8_e32 v[76:77], v29
	v_cvt_pk_f32_fp8_sdwa v[78:79], v29 src0_sel:WORD_1
	v_cvt_pk_f32_fp8_e32 v[80:81], v30
	v_cvt_pk_f32_fp8_sdwa v[82:83], v30 src0_sel:WORD_1
	v_cvt_pk_f32_fp8_e32 v[84:85], v31
	v_cvt_pk_f32_fp8_sdwa v[86:87], v31 src0_sel:WORD_1
	v_pk_mul_f32 v[190:191], v[72:73], v[88:89]
	v_pk_fma_f32 v[190:191], v[74:75], v[90:91], v[190:191]
	v_pk_fma_f32 v[190:191], v[76:77], v[92:93], v[190:191]
	v_pk_fma_f32 v[190:191], v[78:79], v[94:95], v[190:191]
	v_pk_fma_f32 v[190:191], v[80:81], v[96:97], v[190:191]
	v_pk_fma_f32 v[190:191], v[82:83], v[98:99], v[190:191]
	v_pk_fma_f32 v[190:191], v[84:85], v[100:101], v[190:191]
	v_pk_fma_f32 v[190:191], v[86:87], v[102:103], v[190:191]
	v_or_b32_e32 v201, v133, v3
	global_load_dwordx4 v[28:31], v201, s[20:21]
	v_add_f32_e32 v117, v190, v191
	s_waitcnt vmcnt(17)
	v_cvt_pk_f32_fp8_e32 v[72:73], v32
	v_cvt_pk_f32_fp8_sdwa v[74:75], v32 src0_sel:WORD_1
	v_cvt_pk_f32_fp8_e32 v[76:77], v33
	v_cvt_pk_f32_fp8_sdwa v[78:79], v33 src0_sel:WORD_1
	v_cvt_pk_f32_fp8_e32 v[80:81], v34
	v_cvt_pk_f32_fp8_sdwa v[82:83], v34 src0_sel:WORD_1
	v_cvt_pk_f32_fp8_e32 v[84:85], v35
	v_cvt_pk_f32_fp8_sdwa v[86:87], v35 src0_sel:WORD_1
	v_pk_mul_f32 v[190:191], v[72:73], v[88:89]
	v_pk_fma_f32 v[190:191], v[74:75], v[90:91], v[190:191]
	v_pk_fma_f32 v[190:191], v[76:77], v[92:93], v[190:191]
	v_pk_fma_f32 v[190:191], v[78:79], v[94:95], v[190:191]
	v_pk_fma_f32 v[190:191], v[80:81], v[96:97], v[190:191]
	v_pk_fma_f32 v[190:191], v[82:83], v[98:99], v[190:191]
	v_pk_fma_f32 v[190:191], v[84:85], v[100:101], v[190:191]
	v_pk_fma_f32 v[190:191], v[86:87], v[102:103], v[190:191]
	v_or_b32_e32 v202, v134, v3
	global_load_dwordx4 v[32:35], v202, s[20:21]
	v_add_f32_e32 v118, v190, v191
	s_waitcnt vmcnt(17)
	v_cvt_pk_f32_fp8_e32 v[72:73], v36
	v_cvt_pk_f32_fp8_sdwa v[74:75], v36 src0_sel:WORD_1
	v_cvt_pk_f32_fp8_e32 v[76:77], v37
	v_cvt_pk_f32_fp8_sdwa v[78:79], v37 src0_sel:WORD_1
	v_cvt_pk_f32_fp8_e32 v[80:81], v38
	v_cvt_pk_f32_fp8_sdwa v[82:83], v38 src0_sel:WORD_1
	v_cvt_pk_f32_fp8_e32 v[84:85], v39
	v_cvt_pk_f32_fp8_sdwa v[86:87], v39 src0_sel:WORD_1
	v_pk_mul_f32 v[190:191], v[72:73], v[88:89]
	v_pk_fma_f32 v[190:191], v[74:75], v[90:91], v[190:191]
	v_pk_fma_f32 v[190:191], v[76:77], v[92:93], v[190:191]
	v_pk_fma_f32 v[190:191], v[78:79], v[94:95], v[190:191]
	v_pk_fma_f32 v[190:191], v[80:81], v[96:97], v[190:191]
	v_pk_fma_f32 v[190:191], v[82:83], v[98:99], v[190:191]
	v_pk_fma_f32 v[190:191], v[84:85], v[100:101], v[190:191]
	v_pk_fma_f32 v[190:191], v[86:87], v[102:103], v[190:191]
	v_or_b32_e32 v203, v135, v3
	global_load_dwordx4 v[36:39], v203, s[20:21]
	v_add_f32_e32 v119, v190, v191
	s_waitcnt vmcnt(17)
	v_cvt_pk_f32_fp8_e32 v[72:73], v40
	v_cvt_pk_f32_fp8_sdwa v[74:75], v40 src0_sel:WORD_1
	v_cvt_pk_f32_fp8_e32 v[76:77], v41
	v_cvt_pk_f32_fp8_sdwa v[78:79], v41 src0_sel:WORD_1
	v_cvt_pk_f32_fp8_e32 v[80:81], v42
	v_cvt_pk_f32_fp8_sdwa v[82:83], v42 src0_sel:WORD_1
	v_cvt_pk_f32_fp8_e32 v[84:85], v43
	v_cvt_pk_f32_fp8_sdwa v[86:87], v43 src0_sel:WORD_1
	v_pk_mul_f32 v[190:191], v[72:73], v[88:89]
	v_pk_fma_f32 v[190:191], v[74:75], v[90:91], v[190:191]
	v_pk_fma_f32 v[190:191], v[76:77], v[92:93], v[190:191]
	v_pk_fma_f32 v[190:191], v[78:79], v[94:95], v[190:191]
	v_pk_fma_f32 v[190:191], v[80:81], v[96:97], v[190:191]
	v_pk_fma_f32 v[190:191], v[82:83], v[98:99], v[190:191]
	v_pk_fma_f32 v[190:191], v[84:85], v[100:101], v[190:191]
	v_pk_fma_f32 v[190:191], v[86:87], v[102:103], v[190:191]
	v_or_b32_e32 v200, v136, v3
	global_load_dwordx4 v[40:43], v200, s[20:21]
	v_add_f32_e32 v120, v190, v191
	s_waitcnt vmcnt(17)
; DI void phase_peer_u(const Params& p, char* smem) {
;     ...
;         float d[16];
; #pragma unroll
;         for (int i = 0; i < 16; i++) {
;           f32x2 uf[8];
;           unpack_fp8x16(R0[i], uf);
;           f32x2 acc2 = uf[0] * xr[0];
; #pragma unroll
;           for (int j = 1; j < 8; j++) acc2 += uf[j] * xr[j];
;           d[i] = acc2.x + acc2.y;
;         }
	v_cvt_pk_f32_fp8_e32 v[72:73], v44
	v_cvt_pk_f32_fp8_sdwa v[74:75], v44 src0_sel:WORD_1
	v_cvt_pk_f32_fp8_e32 v[76:77], v45
	v_cvt_pk_f32_fp8_sdwa v[78:79], v45 src0_sel:WORD_1
	v_cvt_pk_f32_fp8_e32 v[80:81], v46
	v_cvt_pk_f32_fp8_sdwa v[82:83], v46 src0_sel:WORD_1
	v_cvt_pk_f32_fp8_e32 v[84:85], v47
	v_cvt_pk_f32_fp8_sdwa v[86:87], v47 src0_sel:WORD_1
	v_pk_mul_f32 v[190:191], v[72:73], v[88:89]
	v_pk_fma_f32 v[190:191], v[74:75], v[90:91], v[190:191]
	v_pk_fma_f32 v[190:191], v[76:77], v[92:93], v[190:191]
	v_pk_fma_f32 v[190:191], v[78:79], v[94:95], v[190:191]
	v_pk_fma_f32 v[190:191], v[80:81], v[96:97], v[190:191]
	v_pk_fma_f32 v[190:191], v[82:83], v[98:99], v[190:191]
	v_pk_fma_f32 v[190:191], v[84:85], v[100:101], v[190:191]
	v_pk_fma_f32 v[190:191], v[86:87], v[102:103], v[190:191]
	v_or_b32_e32 v201, v137, v3
	global_load_dwordx4 v[44:47], v201, s[20:21]
	v_add_f32_e32 v121, v190, v191
	s_waitcnt vmcnt(17)
	v_cvt_pk_f32_fp8_e32 v[72:73], v48
	v_cvt_pk_f32_fp8_sdwa v[74:75], v48 src0_sel:WORD_1
	v_cvt_pk_f32_fp8_e32 v[76:77], v49
	v_cvt_pk_f32_fp8_sdwa v[78:79], v49 src0_sel:WORD_1
	v_cvt_pk_f32_fp8_e32 v[80:81], v50
	v_cvt_pk_f32_fp8_sdwa v[82:83], v50 src0_sel:WORD_1
	v_cvt_pk_f32_fp8_e32 v[84:85], v51
	v_cvt_pk_f32_fp8_sdwa v[86:87], v51 src0_sel:WORD_1
	v_pk_mul_f32 v[190:191], v[72:73], v[88:89]
	v_pk_fma_f32 v[190:191], v[74:75], v[90:91], v[190:191]
	v_pk_fma_f32 v[190:191], v[76:77], v[92:93], v[190:191]
	v_pk_fma_f32 v[190:191], v[78:79], v[94:95], v[190:191]
	v_pk_fma_f32 v[190:191], v[80:81], v[96:97], v[190:191]
	v_pk_fma_f32 v[190:191], v[82:83], v[98:99], v[190:191]
	v_pk_fma_f32 v[190:191], v[84:85], v[100:101], v[190:191]
	v_pk_fma_f32 v[190:191], v[86:87], v[102:103], v[190:191]
	v_or_b32_e32 v202, v138, v3
	global_load_dwordx4 v[48:51], v202, s[20:21]
	v_add_f32_e32 v122, v190, v191
	s_waitcnt vmcnt(17)
	v_cvt_pk_f32_fp8_e32 v[72:73], v52
	v_cvt_pk_f32_fp8_sdwa v[74:75], v52 src0_sel:WORD_1
	v_cvt_pk_f32_fp8_e32 v[76:77], v53
	v_cvt_pk_f32_fp8_sdwa v[78:79], v53 src0_sel:WORD_1
	v_cvt_pk_f32_fp8_e32 v[80:81], v54
	v_cvt_pk_f32_fp8_sdwa v[82:83], v54 src0_sel:WORD_1
	v_cvt_pk_f32_fp8_e32 v[84:85], v55
	v_cvt_pk_f32_fp8_sdwa v[86:87], v55 src0_sel:WORD_1
	v_pk_mul_f32 v[190:191], v[72:73], v[88:89]
	v_pk_fma_f32 v[190:191], v[74:75], v[90:91], v[190:191]
	v_pk_fma_f32 v[190:191], v[76:77], v[92:93], v[190:191]
	v_pk_fma_f32 v[190:191], v[78:79], v[94:95], v[190:191]
	v_pk_fma_f32 v[190:191], v[80:81], v[96:97], v[190:191]
	v_pk_fma_f32 v[190:191], v[82:83], v[98:99], v[190:191]
	v_pk_fma_f32 v[190:191], v[84:85], v[100:101], v[190:191]
	v_pk_fma_f32 v[190:191], v[86:87], v[102:103], v[190:191]
	v_or_b32_e32 v203, v139, v3
	global_load_dwordx4 v[52:55], v203, s[20:21]
	v_add_f32_e32 v123, v190, v191
	s_waitcnt vmcnt(17)
	v_cvt_pk_f32_fp8_e32 v[72:73], v56
	v_cvt_pk_f32_fp8_sdwa v[74:75], v56 src0_sel:WORD_1
	v_cvt_pk_f32_fp8_e32 v[76:77], v57
	v_cvt_pk_f32_fp8_sdwa v[78:79], v57 src0_sel:WORD_1
	v_cvt_pk_f32_fp8_e32 v[80:81], v58
	v_cvt_pk_f32_fp8_sdwa v[82:83], v58 src0_sel:WORD_1
	v_cvt_pk_f32_fp8_e32 v[84:85], v59
	v_cvt_pk_f32_fp8_sdwa v[86:87], v59 src0_sel:WORD_1
	v_pk_mul_f32 v[190:191], v[72:73], v[88:89]
	v_pk_fma_f32 v[190:191], v[74:75], v[90:91], v[190:191]
	v_pk_fma_f32 v[190:191], v[76:77], v[92:93], v[190:191]
	v_pk_fma_f32 v[190:191], v[78:79], v[94:95], v[190:191]
	v_pk_fma_f32 v[190:191], v[80:81], v[96:97], v[190:191]
	v_pk_fma_f32 v[190:191], v[82:83], v[98:99], v[190:191]
	v_pk_fma_f32 v[190:191], v[84:85], v[100:101], v[190:191]
	v_pk_fma_f32 v[190:191], v[86:87], v[102:103], v[190:191]
	v_or_b32_e32 v200, v140, v3
	global_load_dwordx4 v[56:59], v200, s[20:21]
	v_add_f32_e32 v124, v190, v191
	s_waitcnt vmcnt(17)
	v_cvt_pk_f32_fp8_e32 v[72:73], v60
	v_cvt_pk_f32_fp8_sdwa v[74:75], v60 src0_sel:WORD_1
	v_cvt_pk_f32_fp8_e32 v[76:77], v61
	v_cvt_pk_f32_fp8_sdwa v[78:79], v61 src0_sel:WORD_1
	v_cvt_pk_f32_fp8_e32 v[80:81], v62
	v_cvt_pk_f32_fp8_sdwa v[82:83], v62 src0_sel:WORD_1
	v_cvt_pk_f32_fp8_e32 v[84:85], v63
	v_cvt_pk_f32_fp8_sdwa v[86:87], v63 src0_sel:WORD_1
	v_pk_mul_f32 v[190:191], v[72:73], v[88:89]
	v_pk_fma_f32 v[190:191], v[74:75], v[90:91], v[190:191]
	v_pk_fma_f32 v[190:191], v[76:77], v[92:93], v[190:191]
	v_pk_fma_f32 v[190:191], v[78:79], v[94:95], v[190:191]
	v_pk_fma_f32 v[190:191], v[80:81], v[96:97], v[190:191]
	v_pk_fma_f32 v[190:191], v[82:83], v[98:99], v[190:191]
	v_pk_fma_f32 v[190:191], v[84:85], v[100:101], v[190:191]
	v_pk_fma_f32 v[190:191], v[86:87], v[102:103], v[190:191]
	v_or_b32_e32 v201, v141, v3
	global_load_dwordx4 v[60:63], v201, s[20:21]
	v_add_f32_e32 v125, v190, v191
	s_waitcnt vmcnt(17)
	v_cvt_pk_f32_fp8_e32 v[72:73], v64
	v_cvt_pk_f32_fp8_sdwa v[74:75], v64 src0_sel:WORD_1
	v_cvt_pk_f32_fp8_e32 v[76:77], v65
	v_cvt_pk_f32_fp8_sdwa v[78:79], v65 src0_sel:WORD_1
	v_cvt_pk_f32_fp8_e32 v[80:81], v66
	v_cvt_pk_f32_fp8_sdwa v[82:83], v66 src0_sel:WORD_1
	v_cvt_pk_f32_fp8_e32 v[84:85], v67
	v_cvt_pk_f32_fp8_sdwa v[86:87], v67 src0_sel:WORD_1
	v_pk_mul_f32 v[190:191], v[72:73], v[88:89]
	v_pk_fma_f32 v[190:191], v[74:75], v[90:91], v[190:191]
	v_pk_fma_f32 v[190:191], v[76:77], v[92:93], v[190:191]
	v_pk_fma_f32 v[190:191], v[78:79], v[94:95], v[190:191]
	v_pk_fma_f32 v[190:191], v[80:81], v[96:97], v[190:191]
	v_pk_fma_f32 v[190:191], v[82:83], v[98:99], v[190:191]
	v_pk_fma_f32 v[190:191], v[84:85], v[100:101], v[190:191]
	v_pk_fma_f32 v[190:191], v[86:87], v[102:103], v[190:191]
	v_or_b32_e32 v202, v142, v3
	global_load_dwordx4 v[64:67], v202, s[20:21]
	v_add_f32_e32 v126, v190, v191
	s_waitcnt vmcnt(17)
; DI float dpp_xor1(float v) { return __builtin_bit_cast(float, __builtin_amdgcn_update_dpp(0, __builtin_bit_cast(int, v), 0xB1, 0xF, 0xF, true)); }
; DI float dpp_xor2(float v) { return __builtin_bit_cast(float, __builtin_amdgcn_update_dpp(0, __builtin_bit_cast(int, v), 0x4E, 0xF, 0xF, true)); }
; DI float swz_xor4(float v) { return __builtin_bit_cast(float, __builtin_amdgcn_ds_swizzle(__builtin_bit_cast(int, v), 0x101F)); }
; DI void phase_peer_u(const Params& p, char* smem) {
;     ...
;         float r8[8], r4[4], r2[2];
; #pragma unroll
;         for (int j = 0; j < 8; j++) r8[j] = (b0 ? d[8 + j] : d[j]) + dpp_xor1(b0 ? d[j] : d[8 + j]);
; #pragma unroll
;         for (int j = 0; j < 4; j++) r4[j] = (b1 ? r8[4 + j] : r8[j]) + dpp_xor2(b1 ? r8[j] : r8[4 + j]);
; #pragma unroll
;         for (int j = 0; j < 2; j++) r2[j] = (b2 ? r4[2 + j] : r4[j]) + swz_xor4(b2 ? r4[j] : r4[2 + j]);
; #pragma unroll
;         for (int j = 0; j < 2; j++) {
;           const int i = ibase + j;
;           pbase[(size_t)t * 128 + 8 * (i & 7) + pg + (i >= 8 ? 64 : 0)] = r2[j];
;         }
; DI float peer_act(const Params& p, size_t idx) {
;   float sacc = 0.f;
; #pragma unroll
;   for (int k = 0; k < 8; k++) sacc += p.part[(size_t)k * T_TOK * 128 + idx];
;   return gelu_tanh(sacc * p.usc[idx]) * p.gates[idx];
; }
	v_cvt_pk_f32_fp8_e32 v[72:73], v68
	v_cvt_pk_f32_fp8_sdwa v[74:75], v68 src0_sel:WORD_1
	v_cvt_pk_f32_fp8_e32 v[76:77], v69
	v_cvt_pk_f32_fp8_sdwa v[78:79], v69 src0_sel:WORD_1
	v_cvt_pk_f32_fp8_e32 v[80:81], v70
	v_cvt_pk_f32_fp8_sdwa v[82:83], v70 src0_sel:WORD_1
	v_cvt_pk_f32_fp8_e32 v[84:85], v71
	v_cvt_pk_f32_fp8_sdwa v[86:87], v71 src0_sel:WORD_1
	v_pk_mul_f32 v[190:191], v[72:73], v[88:89]
	v_pk_fma_f32 v[190:191], v[74:75], v[90:91], v[190:191]
	v_pk_fma_f32 v[190:191], v[76:77], v[92:93], v[190:191]
	v_pk_fma_f32 v[190:191], v[78:79], v[94:95], v[190:191]
	v_pk_fma_f32 v[190:191], v[80:81], v[96:97], v[190:191]
	v_pk_fma_f32 v[190:191], v[82:83], v[98:99], v[190:191]
	v_pk_fma_f32 v[190:191], v[84:85], v[100:101], v[190:191]
	v_pk_fma_f32 v[190:191], v[86:87], v[102:103], v[190:191]
	v_or_b32_e32 v203, v143, v3
	global_load_dwordx4 v[68:71], v203, s[20:21]
	v_add_f32_e32 v127, v190, v191
	s_add_u32 s24, s17, 2
	s_and_b32 s24, s24, 7
	s_lshl_b32 s24, s24, 9
	v_add_u32_e32 v233, s24, v228
	ds_read_b128 v[128:131], v233 offset:4096
	ds_read_b128 v[132:135], v233 offset:4112
	ds_read_b128 v[136:139], v233 offset:4128
	ds_read_b128 v[140:143], v233 offset:4144
	v_cndmask_b32_e64 v160, v120, v112, s[60:61]
	v_cndmask_b32_e64 v168, v112, v120, s[60:61]
	v_cndmask_b32_e64 v161, v121, v113, s[60:61]
	v_cndmask_b32_e64 v169, v113, v121, s[60:61]
	v_cndmask_b32_e64 v162, v122, v114, s[60:61]
	v_cndmask_b32_e64 v170, v114, v122, s[60:61]
	v_cndmask_b32_e64 v163, v123, v115, s[60:61]
	v_cndmask_b32_e64 v171, v115, v123, s[60:61]
	v_cndmask_b32_e64 v164, v124, v116, s[60:61]
	v_cndmask_b32_e64 v172, v116, v124, s[60:61]
	v_cndmask_b32_e64 v165, v125, v117, s[60:61]
	v_cndmask_b32_e64 v173, v117, v125, s[60:61]
	v_cndmask_b32_e64 v166, v126, v118, s[60:61]
	v_cndmask_b32_e64 v174, v118, v126, s[60:61]
	v_cndmask_b32_e64 v167, v127, v119, s[60:61]
	v_cndmask_b32_e64 v175, v119, v127, s[60:61]
	v_add_f32_dpp v160, v168, v160 quad_perm:[1,0,3,2] row_mask:0xf bank_mask:0xf
	v_add_f32_dpp v161, v169, v161 quad_perm:[1,0,3,2] row_mask:0xf bank_mask:0xf
	v_add_f32_dpp v162, v170, v162 quad_perm:[1,0,3,2] row_mask:0xf bank_mask:0xf
	v_add_f32_dpp v163, v171, v163 quad_perm:[1,0,3,2] row_mask:0xf bank_mask:0xf
	v_add_f32_dpp v164, v172, v164 quad_perm:[1,0,3,2] row_mask:0xf bank_mask:0xf
	v_add_f32_dpp v165, v173, v165 quad_perm:[1,0,3,2] row_mask:0xf bank_mask:0xf
	v_add_f32_dpp v166, v174, v166 quad_perm:[1,0,3,2] row_mask:0xf bank_mask:0xf
	v_add_f32_dpp v167, v175, v167 quad_perm:[1,0,3,2] row_mask:0xf bank_mask:0xf
	v_cndmask_b32_e64 v176, v164, v160, s[62:63]
	v_cndmask_b32_e64 v180, v160, v164, s[62:63]
	v_cndmask_b32_e64 v177, v165, v161, s[62:63]
	v_cndmask_b32_e64 v181, v161, v165, s[62:63]
	v_cndmask_b32_e64 v178, v166, v162, s[62:63]
	v_cndmask_b32_e64 v182, v162, v166, s[62:63]
	v_cndmask_b32_e64 v179, v167, v163, s[62:63]
	v_cndmask_b32_e64 v183, v163, v167, s[62:63]
	s_nop 0
	v_add_f32_dpp v176, v180, v176 quad_perm:[2,3,0,1] row_mask:0xf bank_mask:0xf
	v_add_f32_dpp v177, v181, v177 quad_perm:[2,3,0,1] row_mask:0xf bank_mask:0xf
	v_add_f32_dpp v178, v182, v178 quad_perm:[2,3,0,1] row_mask:0xf bank_mask:0xf
	v_add_f32_dpp v179, v183, v179 quad_perm:[2,3,0,1] row_mask:0xf bank_mask:0xf
	v_cndmask_b32_e64 v184, v178, v176, s[64:65]
	v_cndmask_b32_e64 v186, v176, v178, s[64:65]
	v_cndmask_b32_e64 v185, v179, v177, s[64:65]
	v_cndmask_b32_e64 v187, v177, v179, s[64:65]
	ds_swizzle_b32 v186, v186 offset:swizzle(SWAP,4)
	ds_swizzle_b32 v187, v187 offset:swizzle(SWAP,4)
	s_and_b32 s24, s17, 7
	s_lshl_b32 s24, s24, 9
	v_add_u32_e32 v232, s24, v241
	s_waitcnt lgkmcnt(0)
	v_add_f32_e32 v184, v184, v186
	v_add_f32_e32 v185, v185, v187
	ds_add_f32 v232, v184 offset:8192
	ds_add_f32 v232, v185 offset:8196
	s_add_u32 s17, s17, 1
	s_cmp_lt_u32 s17, 64
	s_cbranch_scc1 .Lpeer_ustep
	s_waitcnt vmcnt(0) lgkmcnt(0)
	s_add_u32 s35, s19, 0
	s_lshl_b32 s35, s35, 9
	s_add_u32 s36, s10, s35
	s_addc_u32 s37, s11, 0
	global_load_dword v142, v239, s[36:37]
	global_load_dword v143, v239, s[36:37] offset:32
	s_add_u32 s36, s12, s35
	s_addc_u32 s37, s13, 0
	global_load_dword v144, v239, s[36:37]
	global_load_dword v145, v239, s[36:37] offset:32
	ds_read_b64 v[140:141], v241 offset:8192
	s_add_u32 s35, s19, 1
	s_lshl_b32 s35, s35, 9
	s_add_u32 s36, s10, s35
	s_addc_u32 s37, s11, 0
	global_load_dword v150, v239, s[36:37]
	global_load_dword v151, v239, s[36:37] offset:32
	s_add_u32 s36, s12, s35
	s_addc_u32 s37, s13, 0
	global_load_dword v152, v239, s[36:37]
	global_load_dword v153, v239, s[36:37] offset:32
	ds_read_b64 v[148:149], v241 offset:8704
	s_add_u32 s35, s19, 2
	s_lshl_b32 s35, s35, 9
	s_add_u32 s36, s10, s35
	s_addc_u32 s37, s11, 0
	global_load_dword v158, v239, s[36:37]
	global_load_dword v159, v239, s[36:37] offset:32
	s_add_u32 s36, s12, s35
	s_addc_u32 s37, s13, 0
	global_load_dword v160, v239, s[36:37]
	global_load_dword v161, v239, s[36:37] offset:32
	ds_read_b64 v[156:157], v241 offset:9216
	s_add_u32 s35, s19, 3
	s_lshl_b32 s35, s35, 9
	s_add_u32 s36, s10, s35
	s_addc_u32 s37, s11, 0
	global_load_dword v166, v239, s[36:37]
	global_load_dword v167, v239, s[36:37] offset:32
	s_add_u32 s36, s12, s35
	s_addc_u32 s37, s13, 0
	global_load_dword v168, v239, s[36:37]
	global_load_dword v169, v239, s[36:37] offset:32
	ds_read_b64 v[164:165], v241 offset:9728
	s_add_u32 s35, s19, 4
	s_lshl_b32 s35, s35, 9
	s_add_u32 s36, s10, s35
	s_addc_u32 s37, s11, 0
	global_load_dword v174, v239, s[36:37]
	global_load_dword v175, v239, s[36:37] offset:32
	s_add_u32 s36, s12, s35
	s_addc_u32 s37, s13, 0
	global_load_dword v176, v239, s[36:37]
	global_load_dword v177, v239, s[36:37] offset:32
	ds_read_b64 v[172:173], v241 offset:10240
	s_add_u32 s35, s19, 5
	s_lshl_b32 s35, s35, 9
	s_add_u32 s36, s10, s35
	s_addc_u32 s37, s11, 0
	global_load_dword v182, v239, s[36:37]
	global_load_dword v183, v239, s[36:37] offset:32
	s_add_u32 s36, s12, s35
	s_addc_u32 s37, s13, 0
	global_load_dword v184, v239, s[36:37]
	global_load_dword v185, v239, s[36:37] offset:32
	ds_read_b64 v[180:181], v241 offset:10752
	s_add_u32 s35, s19, 6
	s_lshl_b32 s35, s35, 9
	s_add_u32 s36, s10, s35
	s_addc_u32 s37, s11, 0
	global_load_dword v190, v239, s[36:37]
	global_load_dword v191, v239, s[36:37] offset:32
	s_add_u32 s36, s12, s35
	s_addc_u32 s37, s13, 0
	global_load_dword v192, v239, s[36:37]
	global_load_dword v193, v239, s[36:37] offset:32
	ds_read_b64 v[188:189], v241 offset:11264
	s_add_u32 s35, s19, 7
	s_lshl_b32 s35, s35, 9
	s_add_u32 s36, s10, s35
	s_addc_u32 s37, s11, 0
	global_load_dword v198, v239, s[36:37]
	global_load_dword v199, v239, s[36:37] offset:32
	s_add_u32 s36, s12, s35
	s_addc_u32 s37, s13, 0
	global_load_dword v200, v239, s[36:37]
	global_load_dword v201, v239, s[36:37] offset:32
	ds_read_b64 v[196:197], v241 offset:11776
	s_waitcnt vmcnt(0) lgkmcnt(0)
; DI float gelu_tanh(float x) {
;   const float u = 0.7978845608028654f * (x + 0.044715f * x * x * x);
;   return x / (1.f + __expf(-2.f * u));
; }
; DI float peer_act(const Params& p, size_t idx) {
;   float sacc = 0.f;
; #pragma unroll
;   for (int k = 0; k < 8; k++) sacc += p.part[(size_t)k * T_TOK * 128 + idx];
;   return gelu_tanh(sacc * p.usc[idx]) * p.gates[idx];
; }
	v_pk_mul_f32 v[140:141], v[142:143], v[140:141]
	v_mul_f32_e32 v204, 0x3d372713, v140
	v_mul_f32_e32 v204, v140, v204
	v_fma_f32 v204, v140, v204, v140
	v_mul_f32_e32 v204, 0x3f4c422a, v204
	v_mul_f32_e32 v204, -2.0, v204
	v_mul_f32_e32 v204, 0x3fb8aa3b, v204
	v_exp_f32_e32 v204, v204
	s_nop 0
	v_add_f32_e32 v205, 1.0, v204
	v_div_scale_f32 v206, s[56:57], v205, v205, v140
	v_rcp_f32_e32 v207, v206
	s_nop 0
	v_fma_f32 v208, -v206, v207, 1.0
	v_fmac_f32_e32 v207, v208, v207
	v_div_scale_f32 v208, vcc, v140, v205, v140
	v_mul_f32_e32 v209, v208, v207
	v_fma_f32 v210, -v206, v209, v208
	v_fmac_f32_e32 v209, v210, v207
	v_fma_f32 v206, -v206, v209, v208
	v_div_fmas_f32 v206, v206, v207, v209
	v_div_fixup_f32 v146, v206, v205, v140
	v_mul_f32_e32 v204, 0x3d372713, v141
	v_mul_f32_e32 v204, v141, v204
	v_fma_f32 v204, v141, v204, v141
	v_mul_f32_e32 v204, 0x3f4c422a, v204
	v_mul_f32_e32 v204, -2.0, v204
	v_mul_f32_e32 v204, 0x3fb8aa3b, v204
	v_exp_f32_e32 v204, v204
	s_nop 0
	v_add_f32_e32 v205, 1.0, v204
	v_div_scale_f32 v206, s[56:57], v205, v205, v141
	v_rcp_f32_e32 v207, v206
	s_nop 0
	v_fma_f32 v208, -v206, v207, 1.0
	v_fmac_f32_e32 v207, v208, v207
	v_div_scale_f32 v208, vcc, v141, v205, v141
	v_mul_f32_e32 v209, v208, v207
	v_fma_f32 v210, -v206, v209, v208
	v_fmac_f32_e32 v209, v210, v207
	v_fma_f32 v206, -v206, v209, v208
	v_div_fmas_f32 v206, v206, v207, v209
	v_div_fixup_f32 v147, v206, v205, v141
	v_mul_f32_e32 v146, v146, v144
	v_mul_f32_e32 v147, v147, v145
	ds_write_b32 v238, v146 offset:0
	ds_write_b32 v238, v147 offset:4
	v_pk_mul_f32 v[148:149], v[150:151], v[148:149]
	v_mul_f32_e32 v204, 0x3d372713, v148
	v_mul_f32_e32 v204, v148, v204
	v_fma_f32 v204, v148, v204, v148
	v_mul_f32_e32 v204, 0x3f4c422a, v204
	v_mul_f32_e32 v204, -2.0, v204
	v_mul_f32_e32 v204, 0x3fb8aa3b, v204
	v_exp_f32_e32 v204, v204
	s_nop 0
	v_add_f32_e32 v205, 1.0, v204
	v_div_scale_f32 v206, s[56:57], v205, v205, v148
	v_rcp_f32_e32 v207, v206
	s_nop 0
	v_fma_f32 v208, -v206, v207, 1.0
	v_fmac_f32_e32 v207, v208, v207
	v_div_scale_f32 v208, vcc, v148, v205, v148
	v_mul_f32_e32 v209, v208, v207
	v_fma_f32 v210, -v206, v209, v208
	v_fmac_f32_e32 v209, v210, v207
	v_fma_f32 v206, -v206, v209, v208
	v_div_fmas_f32 v206, v206, v207, v209
	v_div_fixup_f32 v154, v206, v205, v148
	v_mul_f32_e32 v204, 0x3d372713, v149
	v_mul_f32_e32 v204, v149, v204
	v_fma_f32 v204, v149, v204, v149
	v_mul_f32_e32 v204, 0x3f4c422a, v204
	v_mul_f32_e32 v204, -2.0, v204
	v_mul_f32_e32 v204, 0x3fb8aa3b, v204
	v_exp_f32_e32 v204, v204
	s_nop 0
	v_add_f32_e32 v205, 1.0, v204
	v_div_scale_f32 v206, s[56:57], v205, v205, v149
	v_rcp_f32_e32 v207, v206
	s_nop 0
	v_fma_f32 v208, -v206, v207, 1.0
	v_fmac_f32_e32 v207, v208, v207
	v_div_scale_f32 v208, vcc, v149, v205, v149
	v_mul_f32_e32 v209, v208, v207
	v_fma_f32 v210, -v206, v209, v208
	v_fmac_f32_e32 v209, v210, v207
	v_fma_f32 v206, -v206, v209, v208
	v_div_fmas_f32 v206, v206, v207, v209
	v_div_fixup_f32 v155, v206, v205, v149
	v_mul_f32_e32 v154, v154, v152
	v_mul_f32_e32 v155, v155, v153
	ds_write_b32 v238, v154 offset:512
	ds_write_b32 v238, v155 offset:516
	v_pk_mul_f32 v[156:157], v[158:159], v[156:157]
	v_mul_f32_e32 v204, 0x3d372713, v156
	v_mul_f32_e32 v204, v156, v204
	v_fma_f32 v204, v156, v204, v156
	v_mul_f32_e32 v204, 0x3f4c422a, v204
	v_mul_f32_e32 v204, -2.0, v204
	v_mul_f32_e32 v204, 0x3fb8aa3b, v204
	v_exp_f32_e32 v204, v204
	s_nop 0
	v_add_f32_e32 v205, 1.0, v204
	v_div_scale_f32 v206, s[56:57], v205, v205, v156
	v_rcp_f32_e32 v207, v206
	s_nop 0
	v_fma_f32 v208, -v206, v207, 1.0
	v_fmac_f32_e32 v207, v208, v207
	v_div_scale_f32 v208, vcc, v156, v205, v156
	v_mul_f32_e32 v209, v208, v207
	v_fma_f32 v210, -v206, v209, v208
	v_fmac_f32_e32 v209, v210, v207
	v_fma_f32 v206, -v206, v209, v208
	v_div_fmas_f32 v206, v206, v207, v209
	v_div_fixup_f32 v162, v206, v205, v156
	v_mul_f32_e32 v204, 0x3d372713, v157
	v_mul_f32_e32 v204, v157, v204
	v_fma_f32 v204, v157, v204, v157
	v_mul_f32_e32 v204, 0x3f4c422a, v204
	v_mul_f32_e32 v204, -2.0, v204
	v_mul_f32_e32 v204, 0x3fb8aa3b, v204
	v_exp_f32_e32 v204, v204
	s_nop 0
	v_add_f32_e32 v205, 1.0, v204
	v_div_scale_f32 v206, s[56:57], v205, v205, v157
	v_rcp_f32_e32 v207, v206
	s_nop 0
	v_fma_f32 v208, -v206, v207, 1.0
	v_fmac_f32_e32 v207, v208, v207
	v_div_scale_f32 v208, vcc, v157, v205, v157
	v_mul_f32_e32 v209, v208, v207
	v_fma_f32 v210, -v206, v209, v208
	v_fmac_f32_e32 v209, v210, v207
	v_fma_f32 v206, -v206, v209, v208
	v_div_fmas_f32 v206, v206, v207, v209
	v_div_fixup_f32 v163, v206, v205, v157
	v_mul_f32_e32 v162, v162, v160
	v_mul_f32_e32 v163, v163, v161
	ds_write_b32 v238, v162 offset:1024
	ds_write_b32 v238, v163 offset:1028
	v_pk_mul_f32 v[164:165], v[166:167], v[164:165]
	v_mul_f32_e32 v204, 0x3d372713, v164
	v_mul_f32_e32 v204, v164, v204
	v_fma_f32 v204, v164, v204, v164
	v_mul_f32_e32 v204, 0x3f4c422a, v204
	v_mul_f32_e32 v204, -2.0, v204
	v_mul_f32_e32 v204, 0x3fb8aa3b, v204
	v_exp_f32_e32 v204, v204
	s_nop 0
	v_add_f32_e32 v205, 1.0, v204
	v_div_scale_f32 v206, s[56:57], v205, v205, v164
	v_rcp_f32_e32 v207, v206
	s_nop 0
	v_fma_f32 v208, -v206, v207, 1.0
	v_fmac_f32_e32 v207, v208, v207
	v_div_scale_f32 v208, vcc, v164, v205, v164
	v_mul_f32_e32 v209, v208, v207
	v_fma_f32 v210, -v206, v209, v208
	v_fmac_f32_e32 v209, v210, v207
	v_fma_f32 v206, -v206, v209, v208
	v_div_fmas_f32 v206, v206, v207, v209
	v_div_fixup_f32 v170, v206, v205, v164
	v_mul_f32_e32 v204, 0x3d372713, v165
	v_mul_f32_e32 v204, v165, v204
	v_fma_f32 v204, v165, v204, v165
	v_mul_f32_e32 v204, 0x3f4c422a, v204
	v_mul_f32_e32 v204, -2.0, v204
	v_mul_f32_e32 v204, 0x3fb8aa3b, v204
; DI float gelu_tanh(float x) {
;   const float u = 0.7978845608028654f * (x + 0.044715f * x * x * x);
;   return x / (1.f + __expf(-2.f * u));
; }
; DI float peer_act(const Params& p, size_t idx) {
;   float sacc = 0.f;
; #pragma unroll
;   for (int k = 0; k < 8; k++) sacc += p.part[(size_t)k * T_TOK * 128 + idx];
;   return gelu_tanh(sacc * p.usc[idx]) * p.gates[idx];
; }
	v_exp_f32_e32 v204, v204
	s_nop 0
	v_add_f32_e32 v205, 1.0, v204
	v_div_scale_f32 v206, s[56:57], v205, v205, v165
	v_rcp_f32_e32 v207, v206
	s_nop 0
	v_fma_f32 v208, -v206, v207, 1.0
	v_fmac_f32_e32 v207, v208, v207
	v_div_scale_f32 v208, vcc, v165, v205, v165
	v_mul_f32_e32 v209, v208, v207
	v_fma_f32 v210, -v206, v209, v208
	v_fmac_f32_e32 v209, v210, v207
	v_fma_f32 v206, -v206, v209, v208
	v_div_fmas_f32 v206, v206, v207, v209
	v_div_fixup_f32 v171, v206, v205, v165
	v_mul_f32_e32 v170, v170, v168
	v_mul_f32_e32 v171, v171, v169
	ds_write_b32 v238, v170 offset:1536
	ds_write_b32 v238, v171 offset:1540
	v_pk_mul_f32 v[172:173], v[174:175], v[172:173]
	v_mul_f32_e32 v204, 0x3d372713, v172
	v_mul_f32_e32 v204, v172, v204
	v_fma_f32 v204, v172, v204, v172
	v_mul_f32_e32 v204, 0x3f4c422a, v204
	v_mul_f32_e32 v204, -2.0, v204
	v_mul_f32_e32 v204, 0x3fb8aa3b, v204
	v_exp_f32_e32 v204, v204
	s_nop 0
	v_add_f32_e32 v205, 1.0, v204
	v_div_scale_f32 v206, s[56:57], v205, v205, v172
	v_rcp_f32_e32 v207, v206
	s_nop 0
	v_fma_f32 v208, -v206, v207, 1.0
	v_fmac_f32_e32 v207, v208, v207
	v_div_scale_f32 v208, vcc, v172, v205, v172
	v_mul_f32_e32 v209, v208, v207
	v_fma_f32 v210, -v206, v209, v208
	v_fmac_f32_e32 v209, v210, v207
	v_fma_f32 v206, -v206, v209, v208
	v_div_fmas_f32 v206, v206, v207, v209
	v_div_fixup_f32 v178, v206, v205, v172
	v_mul_f32_e32 v204, 0x3d372713, v173
	v_mul_f32_e32 v204, v173, v204
	v_fma_f32 v204, v173, v204, v173
	v_mul_f32_e32 v204, 0x3f4c422a, v204
	v_mul_f32_e32 v204, -2.0, v204
	v_mul_f32_e32 v204, 0x3fb8aa3b, v204
	v_exp_f32_e32 v204, v204
	s_nop 0
	v_add_f32_e32 v205, 1.0, v204
	v_div_scale_f32 v206, s[56:57], v205, v205, v173
	v_rcp_f32_e32 v207, v206
	s_nop 0
	v_fma_f32 v208, -v206, v207, 1.0
	v_fmac_f32_e32 v207, v208, v207
	v_div_scale_f32 v208, vcc, v173, v205, v173
	v_mul_f32_e32 v209, v208, v207
	v_fma_f32 v210, -v206, v209, v208
	v_fmac_f32_e32 v209, v210, v207
	v_fma_f32 v206, -v206, v209, v208
	v_div_fmas_f32 v206, v206, v207, v209
	v_div_fixup_f32 v179, v206, v205, v173
	v_mul_f32_e32 v178, v178, v176
	v_mul_f32_e32 v179, v179, v177
	ds_write_b32 v238, v178 offset:2048
	ds_write_b32 v238, v179 offset:2052
	v_pk_mul_f32 v[180:181], v[182:183], v[180:181]
	v_mul_f32_e32 v204, 0x3d372713, v180
	v_mul_f32_e32 v204, v180, v204
	v_fma_f32 v204, v180, v204, v180
	v_mul_f32_e32 v204, 0x3f4c422a, v204
	v_mul_f32_e32 v204, -2.0, v204
	v_mul_f32_e32 v204, 0x3fb8aa3b, v204
	v_exp_f32_e32 v204, v204
	s_nop 0
	v_add_f32_e32 v205, 1.0, v204
	v_div_scale_f32 v206, s[56:57], v205, v205, v180
	v_rcp_f32_e32 v207, v206
	s_nop 0
	v_fma_f32 v208, -v206, v207, 1.0
	v_fmac_f32_e32 v207, v208, v207
	v_div_scale_f32 v208, vcc, v180, v205, v180
	v_mul_f32_e32 v209, v208, v207
	v_fma_f32 v210, -v206, v209, v208
	v_fmac_f32_e32 v209, v210, v207
	v_fma_f32 v206, -v206, v209, v208
	v_div_fmas_f32 v206, v206, v207, v209
	v_div_fixup_f32 v186, v206, v205, v180
	v_mul_f32_e32 v204, 0x3d372713, v181
	v_mul_f32_e32 v204, v181, v204
	v_fma_f32 v204, v181, v204, v181
	v_mul_f32_e32 v204, 0x3f4c422a, v204
	v_mul_f32_e32 v204, -2.0, v204
	v_mul_f32_e32 v204, 0x3fb8aa3b, v204
	v_exp_f32_e32 v204, v204
	s_nop 0
	v_add_f32_e32 v205, 1.0, v204
	v_div_scale_f32 v206, s[56:57], v205, v205, v181
	v_rcp_f32_e32 v207, v206
	s_nop 0
	v_fma_f32 v208, -v206, v207, 1.0
	v_fmac_f32_e32 v207, v208, v207
	v_div_scale_f32 v208, vcc, v181, v205, v181
	v_mul_f32_e32 v209, v208, v207
	v_fma_f32 v210, -v206, v209, v208
	v_fmac_f32_e32 v209, v210, v207
	v_fma_f32 v206, -v206, v209, v208
	v_div_fmas_f32 v206, v206, v207, v209
	v_div_fixup_f32 v187, v206, v205, v181
	v_mul_f32_e32 v186, v186, v184
	v_mul_f32_e32 v187, v187, v185
	ds_write_b32 v238, v186 offset:2560
	ds_write_b32 v238, v187 offset:2564
	v_pk_mul_f32 v[188:189], v[190:191], v[188:189]
	v_mul_f32_e32 v204, 0x3d372713, v188
	v_mul_f32_e32 v204, v188, v204
	v_fma_f32 v204, v188, v204, v188
	v_mul_f32_e32 v204, 0x3f4c422a, v204
	v_mul_f32_e32 v204, -2.0, v204
	v_mul_f32_e32 v204, 0x3fb8aa3b, v204
	v_exp_f32_e32 v204, v204
	s_nop 0
	v_add_f32_e32 v205, 1.0, v204
	v_div_scale_f32 v206, s[56:57], v205, v205, v188
	v_rcp_f32_e32 v207, v206
	s_nop 0
	v_fma_f32 v208, -v206, v207, 1.0
	v_fmac_f32_e32 v207, v208, v207
	v_div_scale_f32 v208, vcc, v188, v205, v188
	v_mul_f32_e32 v209, v208, v207
	v_fma_f32 v210, -v206, v209, v208
	v_fmac_f32_e32 v209, v210, v207
	v_fma_f32 v206, -v206, v209, v208
	v_div_fmas_f32 v206, v206, v207, v209
	v_div_fixup_f32 v194, v206, v205, v188
	v_mul_f32_e32 v204, 0x3d372713, v189
	v_mul_f32_e32 v204, v189, v204
	v_fma_f32 v204, v189, v204, v189
	v_mul_f32_e32 v204, 0x3f4c422a, v204
	v_mul_f32_e32 v204, -2.0, v204
	v_mul_f32_e32 v204, 0x3fb8aa3b, v204
	v_exp_f32_e32 v204, v204
	s_nop 0
	v_add_f32_e32 v205, 1.0, v204
	v_div_scale_f32 v206, s[56:57], v205, v205, v189
	v_rcp_f32_e32 v207, v206
	s_nop 0
	v_fma_f32 v208, -v206, v207, 1.0
	v_fmac_f32_e32 v207, v208, v207
	v_div_scale_f32 v208, vcc, v189, v205, v189
	v_mul_f32_e32 v209, v208, v207
	v_fma_f32 v210, -v206, v209, v208
	v_fmac_f32_e32 v209, v210, v207
	v_fma_f32 v206, -v206, v209, v208
	v_div_fmas_f32 v206, v206, v207, v209
	v_div_fixup_f32 v195, v206, v205, v189
	v_mul_f32_e32 v194, v194, v192
	v_mul_f32_e32 v195, v195, v193
	ds_write_b32 v238, v194 offset:3072
	ds_write_b32 v238, v195 offset:3076
	v_pk_mul_f32 v[196:197], v[198:199], v[196:197]
	v_mul_f32_e32 v204, 0x3d372713, v196
	v_mul_f32_e32 v204, v196, v204
	v_fma_f32 v204, v196, v204, v196
	v_mul_f32_e32 v204, 0x3f4c422a, v204
	v_mul_f32_e32 v204, -2.0, v204
	v_mul_f32_e32 v204, 0x3fb8aa3b, v204
	v_exp_f32_e32 v204, v204
	s_nop 0
	v_add_f32_e32 v205, 1.0, v204
	v_div_scale_f32 v206, s[56:57], v205, v205, v196
	v_rcp_f32_e32 v207, v206
	s_nop 0
	v_fma_f32 v208, -v206, v207, 1.0
	v_fmac_f32_e32 v207, v208, v207
	v_div_scale_f32 v208, vcc, v196, v205, v196
	v_mul_f32_e32 v209, v208, v207
	v_fma_f32 v210, -v206, v209, v208
	v_fmac_f32_e32 v209, v210, v207
	v_fma_f32 v206, -v206, v209, v208
	v_div_fmas_f32 v206, v206, v207, v209
	v_div_fixup_f32 v202, v206, v205, v196
	v_mul_f32_e32 v204, 0x3d372713, v197
	v_mul_f32_e32 v204, v197, v204
	v_fma_f32 v204, v197, v204, v197
	v_mul_f32_e32 v204, 0x3f4c422a, v204
	v_mul_f32_e32 v204, -2.0, v204
	v_mul_f32_e32 v204, 0x3fb8aa3b, v204
	v_exp_f32_e32 v204, v204
	s_nop 0
	v_add_f32_e32 v205, 1.0, v204
	v_div_scale_f32 v206, s[56:57], v205, v205, v197
	v_rcp_f32_e32 v207, v206
	s_nop 0
	v_fma_f32 v208, -v206, v207, 1.0
	v_fmac_f32_e32 v207, v208, v207
	v_div_scale_f32 v208, vcc, v197, v205, v197
	v_mul_f32_e32 v209, v208, v207
	v_fma_f32 v210, -v206, v209, v208
	v_fmac_f32_e32 v209, v210, v207
	v_fma_f32 v206, -v206, v209, v208
	v_div_fmas_f32 v206, v206, v207, v209
	v_div_fixup_f32 v203, v206, v205, v197
	v_mul_f32_e32 v202, v202, v200
	v_mul_f32_e32 v203, v203, v201
	ds_write_b32 v238, v202 offset:3584
	ds_write_b32 v238, v203 offset:3588
	s_waitcnt lgkmcnt(0)
; DI void phase_peer_v(const Params& p, char* smem) {
;     ...
;       u32x4 R0[16], R1[16];
; #pragma unroll
;       for (int i = 0; i < 16; i++) {
;         const int e = __shfl(i < 8 ? e0a : e0b, 8 * (i & 7) + pg);
;         R0[i] = *(const u32x4*)(vbase + (size_t)e * 128);
;       }
	ds_read_b128 v[120:123], v228 offset:4096
	ds_read_b128 v[124:127], v228 offset:4112
	ds_read_b128 v[128:131], v228 offset:4128
	ds_read_b128 v[132:135], v228 offset:4144
	s_lshl_b32 s24, s16, 21
	s_add_u32 s20, s6, s24
	s_addc_u32 s21, s7, 0
	s_waitcnt lgkmcnt(0)
	v_or_b32_e32 v136, v120, v3
	global_load_dwordx4 v[8:11], v136, s[20:21]
	v_or_b32_e32 v137, v121, v3
	global_load_dwordx4 v[12:15], v137, s[20:21]
	v_or_b32_e32 v235, v122, v3
	global_load_dwordx4 v[16:19], v235, s[20:21]
	v_or_b32_e32 v236, v123, v3
	global_load_dwordx4 v[20:23], v236, s[20:21]
	v_or_b32_e32 v136, v124, v3
	global_load_dwordx4 v[24:27], v136, s[20:21]
	v_or_b32_e32 v137, v125, v3
	global_load_dwordx4 v[28:31], v137, s[20:21]
	v_or_b32_e32 v235, v126, v3
	global_load_dwordx4 v[32:35], v235, s[20:21]
	v_or_b32_e32 v236, v127, v3
	global_load_dwordx4 v[36:39], v236, s[20:21]
	v_or_b32_e32 v136, v128, v3
	global_load_dwordx4 v[40:43], v136, s[20:21]
	v_or_b32_e32 v137, v129, v3
	global_load_dwordx4 v[44:47], v137, s[20:21]
	v_or_b32_e32 v235, v130, v3
	global_load_dwordx4 v[48:51], v235, s[20:21]
	v_or_b32_e32 v236, v131, v3
	global_load_dwordx4 v[52:55], v236, s[20:21]
	v_or_b32_e32 v136, v132, v3
	global_load_dwordx4 v[56:59], v136, s[20:21]
	v_or_b32_e32 v137, v133, v3
	global_load_dwordx4 v[60:63], v137, s[20:21]
	v_or_b32_e32 v235, v134, v3
	global_load_dwordx4 v[64:67], v235, s[20:21]
	v_or_b32_e32 v236, v135, v3
	global_load_dwordx4 v[68:71], v236, s[20:21]
	global_load_dword v234, v231, s[4:5]
	ds_read_b128 v[104:107], v228
	ds_read_b128 v[108:111], v228 offset:16
	ds_read_b128 v[112:115], v228 offset:32
	ds_read_b128 v[116:119], v228 offset:48
	ds_read_b128 v[120:123], v228 offset:4608
	ds_read_b128 v[124:127], v228 offset:4624
	ds_read_b128 v[128:131], v228 offset:4640
	ds_read_b128 v[132:135], v228 offset:4656
	s_mov_b32 s17, 0
	s_waitcnt lgkmcnt(0)
